# GEMM k-loops: 26 M0-hazard s_nop removed from the read phases by issuing the M0 write ahead of the DMA address add (even count per phase, loop heads and attention loops re-padded to their old placemen
# speedup vs baseline: 1.0004x; 1.0004x over previous
.LBB0_145:
	s_add_u32 s27, s50, 0x100
	s_addc_u32 s56, s51, 0
	s_mov_b32 s57, -2
	s_waitcnt lgkmcnt(0)
	ds_read_b128 v[128:131], v188
	ds_read_b128 v[132:135], v188 offset:1024
	ds_read_b128 v[136:139], v188 offset:2048
	ds_read_b128 v[140:143], v188 offset:3072
	ds_read_b128 v[144:147], v189
	ds_read_b128 v[148:151], v189 offset:1024
	ds_read_b128 v[176:179], v189 offset:2048
	ds_read_b128 v[180:183], v189 offset:3072
	s_add_u32 s50, s48, 0x100
	s_addc_u32 s51, s49, 0
	s_cmp_eq_u32 s57, 28
	s_cselect_b32 s55, s21, s51
	s_cselect_b32 s54, s20, s50
	s_cselect_b32 s53, s23, s56
	s_cselect_b32 s52, s22, s27
	v_lshl_add_u64 v[184:185], s[48:49], 0, v[170:171]
	s_add_i32 m0, s60, 0xc000
	ds_read_b128 v[194:197], v190
	ds_read_b128 v[198:201], v190 offset:1024
	ds_read_b128 v[202:205], v190 offset:2048
	ds_read_b128 v[206:209], v190 offset:3072
	ds_read_b128 v[210:213], v190 offset:4096
	ds_read_b128 v[214:217], v190 offset:5120
	ds_read_b128 v[218:221], v190 offset:6144
	ds_read_b128 v[222:225], v190 offset:7168
	global_load_lds_dwordx4 v[184:185], off
	v_lshl_add_u64 v[184:185], s[48:49], 0, v[172:173]
	s_add_i32 m0, s60, 0xe000
	s_nop 0
	global_load_lds_dwordx4 v[184:185], off
	s_waitcnt vmcnt(8) lgkmcnt(0)
	s_setprio 1
	s_barrier
	v_mfma_f32_16x16x32_bf16 v[120:123], v[128:131], v[194:197], 0
	v_mfma_f32_16x16x32_bf16 v[124:127], v[136:139], v[194:197], 0
	v_mfma_f32_16x16x32_bf16 v[108:111], v[128:131], v[202:205], 0
	v_mfma_f32_16x16x32_bf16 v[104:107], v[136:139], v[202:205], 0
	v_mfma_f32_16x16x32_bf16 v[92:95], v[128:131], v[210:213], 0
	v_mfma_f32_16x16x32_bf16 v[88:91], v[136:139], v[210:213], 0
	v_mfma_f32_16x16x32_bf16 v[76:79], v[128:131], v[218:221], 0
	v_mfma_f32_16x16x32_bf16 v[72:75], v[136:139], v[218:221], 0
	v_mfma_f32_16x16x32_bf16 v[120:123], v[132:135], v[198:201], v[120:123]
	v_mfma_f32_16x16x32_bf16 v[124:127], v[140:143], v[198:201], v[124:127]
	v_mfma_f32_16x16x32_bf16 v[108:111], v[132:135], v[206:209], v[108:111]
	v_mfma_f32_16x16x32_bf16 v[104:107], v[140:143], v[206:209], v[104:107]
	v_mfma_f32_16x16x32_bf16 v[92:95], v[132:135], v[214:217], v[92:95]
	v_mfma_f32_16x16x32_bf16 v[88:91], v[140:143], v[214:217], v[88:91]
	v_mfma_f32_16x16x32_bf16 v[76:79], v[132:135], v[222:225], v[76:79]
	v_mfma_f32_16x16x32_bf16 v[72:75], v[140:143], v[222:225], v[72:75]
	s_setprio 0
	s_setprio 1
	v_mfma_f32_16x16x32_bf16 v[112:115], v[144:147], v[194:197], 0
	v_mfma_f32_16x16x32_bf16 v[116:119], v[176:179], v[194:197], 0
	v_mfma_f32_16x16x32_bf16 v[100:103], v[144:147], v[202:205], 0
	v_mfma_f32_16x16x32_bf16 v[96:99], v[176:179], v[202:205], 0
	v_mfma_f32_16x16x32_bf16 v[84:87], v[144:147], v[210:213], 0
	v_mfma_f32_16x16x32_bf16 v[80:83], v[176:179], v[210:213], 0
	v_mfma_f32_16x16x32_bf16 v[68:71], v[144:147], v[218:221], 0
	v_mfma_f32_16x16x32_bf16 v[64:67], v[176:179], v[218:221], 0
	v_mfma_f32_16x16x32_bf16 v[112:115], v[148:151], v[198:201], v[112:115]
	v_mfma_f32_16x16x32_bf16 v[116:119], v[180:183], v[198:201], v[116:119]
	v_mfma_f32_16x16x32_bf16 v[100:103], v[148:151], v[206:209], v[100:103]
	v_mfma_f32_16x16x32_bf16 v[96:99], v[180:183], v[206:209], v[96:99]
	v_mfma_f32_16x16x32_bf16 v[84:87], v[148:151], v[214:217], v[84:87]
	v_mfma_f32_16x16x32_bf16 v[80:83], v[180:183], v[214:217], v[80:83]
	v_mfma_f32_16x16x32_bf16 v[68:71], v[148:151], v[222:225], v[68:71]
	v_mfma_f32_16x16x32_bf16 v[64:67], v[180:183], v[222:225], v[64:67]
	s_barrier
	s_setprio 0
	s_add_i32 s48, s71, s3
	v_lshl_add_u64 v[184:185], s[52:53], 0, v[154:155]
	s_mov_b32 m0, s48
	ds_read_b128 v[194:197], v190 offset:16384
	ds_read_b128 v[198:201], v190 offset:17408
	ds_read_b128 v[202:205], v190 offset:18432
	ds_read_b128 v[206:209], v190 offset:19456
	ds_read_b128 v[210:213], v190 offset:20480
	ds_read_b128 v[214:217], v190 offset:21504
	ds_read_b128 v[218:221], v190 offset:22528
	ds_read_b128 v[222:225], v190 offset:23552
	global_load_lds_dwordx4 v[184:185], off
	s_add_i32 m0, s48, 0x2000
	s_add_u32 s48, s52, 0x80000
	v_lshl_add_u64 v[226:227], s[52:53], 0, v[158:159]
	s_addc_u32 s49, s53, 0
	s_add_i32 s58, s72, s3
	global_load_lds_dwordx4 v[226:227], off
	v_lshl_add_u64 v[228:229], s[48:49], 0, v[154:155]
	s_mov_b32 m0, s58
	v_lshl_add_u64 v[230:231], s[54:55], 0, v[156:157]
	global_load_lds_dwordx4 v[228:229], off
	s_add_i32 m0, s58, 0x2000
	v_lshl_add_u64 v[228:229], s[48:49], 0, v[158:159]
	global_load_lds_dwordx4 v[228:229], off
	s_mov_b32 m0, s60
	v_lshl_add_u64 v[228:229], s[54:55], 0, v[152:153]
	global_load_lds_dwordx4 v[228:229], off
	s_mov_b32 m0, s61
	s_nop 0
	global_load_lds_dwordx4 v[230:231], off
	s_waitcnt vmcnt(8) lgkmcnt(0)
	s_setprio 1
	s_barrier
	v_mfma_f32_16x16x32_bf16 v[60:63], v[128:131], v[194:197], 0
	v_mfma_f32_16x16x32_bf16 v[56:59], v[136:139], v[194:197], 0
	v_mfma_f32_16x16x32_bf16 v[44:47], v[128:131], v[202:205], 0
	v_mfma_f32_16x16x32_bf16 v[40:43], v[136:139], v[202:205], 0
	v_mfma_f32_16x16x32_bf16 v[28:31], v[128:131], v[210:213], 0
	v_mfma_f32_16x16x32_bf16 v[24:27], v[136:139], v[210:213], 0
	v_mfma_f32_16x16x32_bf16 v[12:15], v[128:131], v[218:221], 0
	v_mfma_f32_16x16x32_bf16 v[8:11], v[136:139], v[218:221], 0
	v_mfma_f32_16x16x32_bf16 v[60:63], v[132:135], v[198:201], v[60:63]
	v_mfma_f32_16x16x32_bf16 v[56:59], v[140:143], v[198:201], v[56:59]
	v_mfma_f32_16x16x32_bf16 v[44:47], v[132:135], v[206:209], v[44:47]
	v_mfma_f32_16x16x32_bf16 v[40:43], v[140:143], v[206:209], v[40:43]
	v_mfma_f32_16x16x32_bf16 v[28:31], v[132:135], v[214:217], v[28:31]
	v_mfma_f32_16x16x32_bf16 v[24:27], v[140:143], v[214:217], v[24:27]
	v_mfma_f32_16x16x32_bf16 v[12:15], v[132:135], v[222:225], v[12:15]
	v_mfma_f32_16x16x32_bf16 v[8:11], v[140:143], v[222:225], v[8:11]
	s_setprio 0
	s_setprio 1
	v_mfma_f32_16x16x32_bf16 v[52:55], v[144:147], v[194:197], 0
	v_mfma_f32_16x16x32_bf16 v[48:51], v[176:179], v[194:197], 0
	v_mfma_f32_16x16x32_bf16 v[36:39], v[144:147], v[202:205], 0
	v_mfma_f32_16x16x32_bf16 v[32:35], v[176:179], v[202:205], 0
	v_mfma_f32_16x16x32_bf16 v[20:23], v[144:147], v[210:213], 0
	v_mfma_f32_16x16x32_bf16 v[16:19], v[176:179], v[210:213], 0
	v_mfma_f32_16x16x32_bf16 v[4:7], v[144:147], v[218:221], 0
	v_mfma_f32_16x16x32_bf16 v[0:3], v[176:179], v[218:221], 0
	v_mfma_f32_16x16x32_bf16 v[52:55], v[148:151], v[198:201], v[52:55]
	v_mfma_f32_16x16x32_bf16 v[48:51], v[180:183], v[198:201], v[48:51]
	v_mfma_f32_16x16x32_bf16 v[36:39], v[148:151], v[206:209], v[36:39]
	v_mfma_f32_16x16x32_bf16 v[32:35], v[180:183], v[206:209], v[32:35]
	v_mfma_f32_16x16x32_bf16 v[20:23], v[148:151], v[214:217], v[20:23]
	v_mfma_f32_16x16x32_bf16 v[16:19], v[180:183], v[214:217], v[16:19]
	v_mfma_f32_16x16x32_bf16 v[4:7], v[148:151], v[222:225], v[4:7]
	v_mfma_f32_16x16x32_bf16 v[0:3], v[180:183], v[222:225], v[0:3]
	s_barrier
	s_setprio 0
	s_branch .Lpeel_mid_p1
	s_nop 0
	s_nop 0
	s_nop 0
	s_nop 0
	s_nop 0
	s_nop 0
.LBB0_146:
	ds_read_b128 v[128:131], v188
	ds_read_b128 v[132:135], v188 offset:1024
	ds_read_b128 v[136:139], v188 offset:2048
	ds_read_b128 v[140:143], v188 offset:3072
	ds_read_b128 v[144:147], v189
	ds_read_b128 v[148:151], v189 offset:1024
	ds_read_b128 v[176:179], v189 offset:2048
	ds_read_b128 v[180:183], v189 offset:3072
	s_add_u32 s50, s48, 0x100
	s_addc_u32 s51, s49, 0
	s_cmp_eq_u32 s57, 28
	s_cselect_b32 s55, s21, s51
	s_cselect_b32 s54, s20, s50
	s_cselect_b32 s53, s23, s56
	s_cselect_b32 s52, s22, s27
	v_lshl_add_u64 v[184:185], s[48:49], 0, v[170:171]
	s_add_i32 m0, s60, 0xc000
	ds_read_b128 v[194:197], v190
	ds_read_b128 v[198:201], v190 offset:1024
	ds_read_b128 v[202:205], v190 offset:2048
	ds_read_b128 v[206:209], v190 offset:3072
	ds_read_b128 v[210:213], v190 offset:4096
	ds_read_b128 v[214:217], v190 offset:5120
	ds_read_b128 v[218:221], v190 offset:6144
	ds_read_b128 v[222:225], v190 offset:7168
	global_load_lds_dwordx4 v[184:185], off
	v_lshl_add_u64 v[184:185], s[48:49], 0, v[172:173]
	s_add_i32 m0, s60, 0xe000
	s_nop 0
	global_load_lds_dwordx4 v[184:185], off
	s_waitcnt vmcnt(8) lgkmcnt(0)
	s_setprio 1
	s_barrier
	v_mfma_f32_16x16x32_bf16 v[120:123], v[128:131], v[194:197], v[120:123]
	v_mfma_f32_16x16x32_bf16 v[124:127], v[136:139], v[194:197], v[124:127]
	v_mfma_f32_16x16x32_bf16 v[108:111], v[128:131], v[202:205], v[108:111]
	v_mfma_f32_16x16x32_bf16 v[104:107], v[136:139], v[202:205], v[104:107]
	v_mfma_f32_16x16x32_bf16 v[92:95], v[128:131], v[210:213], v[92:95]
	v_mfma_f32_16x16x32_bf16 v[88:91], v[136:139], v[210:213], v[88:91]
	v_mfma_f32_16x16x32_bf16 v[76:79], v[128:131], v[218:221], v[76:79]
	v_mfma_f32_16x16x32_bf16 v[72:75], v[136:139], v[218:221], v[72:75]
	v_mfma_f32_16x16x32_bf16 v[120:123], v[132:135], v[198:201], v[120:123]
	v_mfma_f32_16x16x32_bf16 v[124:127], v[140:143], v[198:201], v[124:127]
	v_mfma_f32_16x16x32_bf16 v[108:111], v[132:135], v[206:209], v[108:111]
	v_mfma_f32_16x16x32_bf16 v[104:107], v[140:143], v[206:209], v[104:107]
	v_mfma_f32_16x16x32_bf16 v[92:95], v[132:135], v[214:217], v[92:95]
	v_mfma_f32_16x16x32_bf16 v[88:91], v[140:143], v[214:217], v[88:91]
	v_mfma_f32_16x16x32_bf16 v[76:79], v[132:135], v[222:225], v[76:79]
	v_mfma_f32_16x16x32_bf16 v[72:75], v[140:143], v[222:225], v[72:75]
	s_setprio 0
	s_setprio 1
	v_mfma_f32_16x16x32_bf16 v[112:115], v[144:147], v[194:197], v[112:115]
	v_mfma_f32_16x16x32_bf16 v[116:119], v[176:179], v[194:197], v[116:119]
	v_mfma_f32_16x16x32_bf16 v[100:103], v[144:147], v[202:205], v[100:103]
	v_mfma_f32_16x16x32_bf16 v[96:99], v[176:179], v[202:205], v[96:99]
	v_mfma_f32_16x16x32_bf16 v[84:87], v[144:147], v[210:213], v[84:87]
	v_mfma_f32_16x16x32_bf16 v[80:83], v[176:179], v[210:213], v[80:83]
	v_mfma_f32_16x16x32_bf16 v[68:71], v[144:147], v[218:221], v[68:71]
	v_mfma_f32_16x16x32_bf16 v[64:67], v[176:179], v[218:221], v[64:67]
	v_mfma_f32_16x16x32_bf16 v[112:115], v[148:151], v[198:201], v[112:115]
	v_mfma_f32_16x16x32_bf16 v[116:119], v[180:183], v[198:201], v[116:119]
	v_mfma_f32_16x16x32_bf16 v[100:103], v[148:151], v[206:209], v[100:103]
	v_mfma_f32_16x16x32_bf16 v[96:99], v[180:183], v[206:209], v[96:99]
	v_mfma_f32_16x16x32_bf16 v[84:87], v[148:151], v[214:217], v[84:87]
	v_mfma_f32_16x16x32_bf16 v[80:83], v[180:183], v[214:217], v[80:83]
	v_mfma_f32_16x16x32_bf16 v[68:71], v[148:151], v[222:225], v[68:71]
	v_mfma_f32_16x16x32_bf16 v[64:67], v[180:183], v[222:225], v[64:67]
	s_barrier
	s_setprio 0
	s_add_i32 s48, s71, s3
	v_lshl_add_u64 v[184:185], s[52:53], 0, v[154:155]
	s_mov_b32 m0, s48
	ds_read_b128 v[194:197], v190 offset:16384
	ds_read_b128 v[198:201], v190 offset:17408
	ds_read_b128 v[202:205], v190 offset:18432
	ds_read_b128 v[206:209], v190 offset:19456
	ds_read_b128 v[210:213], v190 offset:20480
	ds_read_b128 v[214:217], v190 offset:21504
	ds_read_b128 v[218:221], v190 offset:22528
	ds_read_b128 v[222:225], v190 offset:23552
	global_load_lds_dwordx4 v[184:185], off
	s_add_i32 m0, s48, 0x2000
	s_add_u32 s48, s52, 0x80000
	v_lshl_add_u64 v[226:227], s[52:53], 0, v[158:159]
	s_addc_u32 s49, s53, 0
	s_add_i32 s58, s72, s3
	global_load_lds_dwordx4 v[226:227], off
	v_lshl_add_u64 v[228:229], s[48:49], 0, v[154:155]
	s_mov_b32 m0, s58
	v_lshl_add_u64 v[230:231], s[54:55], 0, v[156:157]
	global_load_lds_dwordx4 v[228:229], off
	s_add_i32 m0, s58, 0x2000
	v_lshl_add_u64 v[228:229], s[48:49], 0, v[158:159]
	global_load_lds_dwordx4 v[228:229], off
	s_mov_b32 m0, s60
	v_lshl_add_u64 v[228:229], s[54:55], 0, v[152:153]
	global_load_lds_dwordx4 v[228:229], off
	s_mov_b32 m0, s61
	s_nop 0
	global_load_lds_dwordx4 v[230:231], off
	s_waitcnt vmcnt(8) lgkmcnt(0)
	s_setprio 1
	s_barrier
	v_mfma_f32_16x16x32_bf16 v[60:63], v[128:131], v[194:197], v[60:63]
	v_mfma_f32_16x16x32_bf16 v[56:59], v[136:139], v[194:197], v[56:59]
	v_mfma_f32_16x16x32_bf16 v[44:47], v[128:131], v[202:205], v[44:47]
	v_mfma_f32_16x16x32_bf16 v[40:43], v[136:139], v[202:205], v[40:43]
	v_mfma_f32_16x16x32_bf16 v[28:31], v[128:131], v[210:213], v[28:31]
	v_mfma_f32_16x16x32_bf16 v[24:27], v[136:139], v[210:213], v[24:27]
	v_mfma_f32_16x16x32_bf16 v[12:15], v[128:131], v[218:221], v[12:15]
	v_mfma_f32_16x16x32_bf16 v[8:11], v[136:139], v[218:221], v[8:11]
	v_mfma_f32_16x16x32_bf16 v[60:63], v[132:135], v[198:201], v[60:63]
	v_mfma_f32_16x16x32_bf16 v[56:59], v[140:143], v[198:201], v[56:59]
	v_mfma_f32_16x16x32_bf16 v[44:47], v[132:135], v[206:209], v[44:47]
	v_mfma_f32_16x16x32_bf16 v[40:43], v[140:143], v[206:209], v[40:43]
	v_mfma_f32_16x16x32_bf16 v[28:31], v[132:135], v[214:217], v[28:31]
	v_mfma_f32_16x16x32_bf16 v[24:27], v[140:143], v[214:217], v[24:27]
	v_mfma_f32_16x16x32_bf16 v[12:15], v[132:135], v[222:225], v[12:15]
	v_mfma_f32_16x16x32_bf16 v[8:11], v[140:143], v[222:225], v[8:11]
	s_setprio 0
	s_setprio 1
	v_mfma_f32_16x16x32_bf16 v[52:55], v[144:147], v[194:197], v[52:55]
	v_mfma_f32_16x16x32_bf16 v[48:51], v[176:179], v[194:197], v[48:51]
	v_mfma_f32_16x16x32_bf16 v[36:39], v[144:147], v[202:205], v[36:39]
	v_mfma_f32_16x16x32_bf16 v[32:35], v[176:179], v[202:205], v[32:35]
	v_mfma_f32_16x16x32_bf16 v[20:23], v[144:147], v[210:213], v[20:23]
	v_mfma_f32_16x16x32_bf16 v[16:19], v[176:179], v[210:213], v[16:19]
	v_mfma_f32_16x16x32_bf16 v[4:7], v[144:147], v[218:221], v[4:7]
	v_mfma_f32_16x16x32_bf16 v[0:3], v[176:179], v[218:221], v[0:3]
	v_mfma_f32_16x16x32_bf16 v[52:55], v[148:151], v[198:201], v[52:55]
	v_mfma_f32_16x16x32_bf16 v[48:51], v[180:183], v[198:201], v[48:51]
	v_mfma_f32_16x16x32_bf16 v[36:39], v[148:151], v[206:209], v[36:39]
	v_mfma_f32_16x16x32_bf16 v[32:35], v[180:183], v[206:209], v[32:35]
	v_mfma_f32_16x16x32_bf16 v[20:23], v[148:151], v[214:217], v[20:23]
	v_mfma_f32_16x16x32_bf16 v[16:19], v[180:183], v[214:217], v[16:19]
	v_mfma_f32_16x16x32_bf16 v[4:7], v[148:151], v[222:225], v[4:7]
	v_mfma_f32_16x16x32_bf16 v[0:3], v[180:183], v[222:225], v[0:3]
	s_barrier
	s_setprio 0
.Lpeel_mid_p1:
	s_add_i32 s58, 0, 0x18000
	s_add_i32 s59, 0, 0x1c000
	v_add_u32_e32 v140, s58, v186
	v_add_u32_e32 v160, s59, v186
	ds_read_b128 v[128:131], v140
	ds_read_b128 v[132:135], v140 offset:1024
	ds_read_b128 v[136:139], v140 offset:2048
	ds_read_b128 v[140:143], v140 offset:3072
	ds_read_b128 v[144:147], v160
	ds_read_b128 v[148:151], v160 offset:1024
	ds_read_b128 v[176:179], v160 offset:2048
	ds_read_b128 v[180:183], v160 offset:3072
	s_add_u32 s48, s54, 0xa0000
	s_addc_u32 s49, s55, 0
	s_mov_b32 m0, s62
	v_lshl_add_u64 v[232:233], s[48:49], 0, v[152:153]
	ds_read_b128 v[194:197], v190 offset:32768
	ds_read_b128 v[198:201], v190 offset:33792
	ds_read_b128 v[202:205], v190 offset:34816
	ds_read_b128 v[206:209], v190 offset:35840
	ds_read_b128 v[210:213], v190 offset:36864
	ds_read_b128 v[214:217], v190 offset:37888
	ds_read_b128 v[218:221], v190 offset:38912
	ds_read_b128 v[222:225], v190 offset:39936
	global_load_lds_dwordx4 v[232:233], off
	v_lshl_add_u64 v[232:233], s[48:49], 0, v[156:157]
	s_mov_b32 m0, s63
	s_nop 0
	global_load_lds_dwordx4 v[232:233], off
	s_waitcnt vmcnt(8) lgkmcnt(0)
	s_setprio 1
	s_barrier
	v_mfma_f32_16x16x32_bf16 v[120:123], v[128:131], v[194:197], v[120:123]
	v_mfma_f32_16x16x32_bf16 v[124:127], v[136:139], v[194:197], v[124:127]
	v_mfma_f32_16x16x32_bf16 v[108:111], v[128:131], v[202:205], v[108:111]
	v_mfma_f32_16x16x32_bf16 v[104:107], v[136:139], v[202:205], v[104:107]
	v_mfma_f32_16x16x32_bf16 v[92:95], v[128:131], v[210:213], v[92:95]
	v_mfma_f32_16x16x32_bf16 v[88:91], v[136:139], v[210:213], v[88:91]
	v_mfma_f32_16x16x32_bf16 v[76:79], v[128:131], v[218:221], v[76:79]
	v_mfma_f32_16x16x32_bf16 v[72:75], v[136:139], v[218:221], v[72:75]
	v_mfma_f32_16x16x32_bf16 v[120:123], v[132:135], v[198:201], v[120:123]
	v_mfma_f32_16x16x32_bf16 v[124:127], v[140:143], v[198:201], v[124:127]
	v_mfma_f32_16x16x32_bf16 v[108:111], v[132:135], v[206:209], v[108:111]
	v_mfma_f32_16x16x32_bf16 v[104:107], v[140:143], v[206:209], v[104:107]
	v_mfma_f32_16x16x32_bf16 v[92:95], v[132:135], v[214:217], v[92:95]
	v_mfma_f32_16x16x32_bf16 v[88:91], v[140:143], v[214:217], v[88:91]
	v_mfma_f32_16x16x32_bf16 v[76:79], v[132:135], v[222:225], v[76:79]
	v_mfma_f32_16x16x32_bf16 v[72:75], v[140:143], v[222:225], v[72:75]
	s_setprio 0
	s_setprio 1
	v_mfma_f32_16x16x32_bf16 v[112:115], v[144:147], v[194:197], v[112:115]
	v_mfma_f32_16x16x32_bf16 v[116:119], v[176:179], v[194:197], v[116:119]
	v_mfma_f32_16x16x32_bf16 v[100:103], v[144:147], v[202:205], v[100:103]
	v_mfma_f32_16x16x32_bf16 v[96:99], v[176:179], v[202:205], v[96:99]
	v_mfma_f32_16x16x32_bf16 v[84:87], v[144:147], v[210:213], v[84:87]
	v_mfma_f32_16x16x32_bf16 v[80:83], v[176:179], v[210:213], v[80:83]
	v_mfma_f32_16x16x32_bf16 v[68:71], v[144:147], v[218:221], v[68:71]
	v_mfma_f32_16x16x32_bf16 v[64:67], v[176:179], v[218:221], v[64:67]
	v_mfma_f32_16x16x32_bf16 v[112:115], v[148:151], v[198:201], v[112:115]
	v_mfma_f32_16x16x32_bf16 v[116:119], v[180:183], v[198:201], v[116:119]
	v_mfma_f32_16x16x32_bf16 v[100:103], v[148:151], v[206:209], v[100:103]
	v_mfma_f32_16x16x32_bf16 v[96:99], v[180:183], v[206:209], v[96:99]
	v_mfma_f32_16x16x32_bf16 v[84:87], v[148:151], v[214:217], v[84:87]
	v_mfma_f32_16x16x32_bf16 v[80:83], v[180:183], v[214:217], v[80:83]
	v_mfma_f32_16x16x32_bf16 v[68:71], v[148:151], v[222:225], v[68:71]
	v_mfma_f32_16x16x32_bf16 v[64:67], v[180:183], v[222:225], v[64:67]
	s_barrier
	s_setprio 0
	s_add_i32 s48, s58, s3
	v_lshl_add_u64 v[184:185], v[184:185], 0, s[14:15]
	s_mov_b32 m0, s48
	ds_read_b128 v[194:197], v190 offset:49152
	ds_read_b128 v[198:201], v190 offset:50176
	ds_read_b128 v[202:205], v190 offset:51200
	ds_read_b128 v[206:209], v190 offset:52224
	ds_read_b128 v[210:213], v190 offset:53248
	ds_read_b128 v[214:217], v190 offset:54272
	ds_read_b128 v[218:221], v190 offset:55296
	ds_read_b128 v[222:225], v190 offset:56320
	global_load_lds_dwordx4 v[184:185], off
	s_add_i32 m0, s48, 0x2000
	s_add_u32 s48, s52, 0x80080
	v_lshl_add_u64 v[184:185], v[226:227], 0, s[14:15]
	s_addc_u32 s49, s53, 0
	s_add_i32 s52, s59, s3
	global_load_lds_dwordx4 v[184:185], off
	s_mov_b32 m0, s52
	v_lshl_add_u64 v[184:185], s[48:49], 0, v[154:155]
	global_load_lds_dwordx4 v[184:185], off
	s_add_i32 m0, s52, 0x2000
	v_lshl_add_u64 v[184:185], s[48:49], 0, v[158:159]
	global_load_lds_dwordx4 v[184:185], off
	s_mov_b32 m0, s66
	v_lshl_add_u64 v[184:185], v[228:229], 0, s[14:15]
	global_load_lds_dwordx4 v[184:185], off
	s_mov_b32 m0, s67
	v_lshl_add_u64 v[184:185], v[230:231], 0, s[14:15]
	global_load_lds_dwordx4 v[184:185], off
	s_waitcnt vmcnt(8) lgkmcnt(0)
	s_setprio 1
	s_barrier
	v_mfma_f32_16x16x32_bf16 v[60:63], v[128:131], v[194:197], v[60:63]
	v_mfma_f32_16x16x32_bf16 v[56:59], v[136:139], v[194:197], v[56:59]
	v_mfma_f32_16x16x32_bf16 v[44:47], v[128:131], v[202:205], v[44:47]
	v_mfma_f32_16x16x32_bf16 v[40:43], v[136:139], v[202:205], v[40:43]
	v_mfma_f32_16x16x32_bf16 v[28:31], v[128:131], v[210:213], v[28:31]
	v_mfma_f32_16x16x32_bf16 v[24:27], v[136:139], v[210:213], v[24:27]
	v_mfma_f32_16x16x32_bf16 v[12:15], v[128:131], v[218:221], v[12:15]
	v_mfma_f32_16x16x32_bf16 v[8:11], v[136:139], v[218:221], v[8:11]
	v_mfma_f32_16x16x32_bf16 v[60:63], v[132:135], v[198:201], v[60:63]
	v_mfma_f32_16x16x32_bf16 v[56:59], v[140:143], v[198:201], v[56:59]
	v_mfma_f32_16x16x32_bf16 v[44:47], v[132:135], v[206:209], v[44:47]
	v_mfma_f32_16x16x32_bf16 v[40:43], v[140:143], v[206:209], v[40:43]
	v_mfma_f32_16x16x32_bf16 v[28:31], v[132:135], v[214:217], v[28:31]
	v_mfma_f32_16x16x32_bf16 v[24:27], v[140:143], v[214:217], v[24:27]
	v_mfma_f32_16x16x32_bf16 v[12:15], v[132:135], v[222:225], v[12:15]
	v_mfma_f32_16x16x32_bf16 v[8:11], v[140:143], v[222:225], v[8:11]
	s_setprio 0
	s_setprio 1
	v_mfma_f32_16x16x32_bf16 v[52:55], v[144:147], v[194:197], v[52:55]
	v_mfma_f32_16x16x32_bf16 v[48:51], v[176:179], v[194:197], v[48:51]
	v_mfma_f32_16x16x32_bf16 v[36:39], v[144:147], v[202:205], v[36:39]
	v_mfma_f32_16x16x32_bf16 v[32:35], v[176:179], v[202:205], v[32:35]
	s_add_i32 s57, s57, 2
	v_mfma_f32_16x16x32_bf16 v[20:23], v[144:147], v[210:213], v[20:23]
	s_add_u32 s27, s27, 0x100
	v_mfma_f32_16x16x32_bf16 v[16:19], v[176:179], v[210:213], v[16:19]
	s_addc_u32 s56, s56, 0
	v_mfma_f32_16x16x32_bf16 v[4:7], v[144:147], v[218:221], v[4:7]
	s_cmp_gt_u32 s57, 29
	v_mfma_f32_16x16x32_bf16 v[0:3], v[176:179], v[218:221], v[0:3]
	s_mov_b64 s[48:49], s[50:51]
	v_mfma_f32_16x16x32_bf16 v[52:55], v[148:151], v[198:201], v[52:55]
	v_mfma_f32_16x16x32_bf16 v[48:51], v[180:183], v[198:201], v[48:51]
	v_mfma_f32_16x16x32_bf16 v[36:39], v[148:151], v[206:209], v[36:39]
	v_mfma_f32_16x16x32_bf16 v[32:35], v[180:183], v[206:209], v[32:35]
	v_mfma_f32_16x16x32_bf16 v[20:23], v[148:151], v[214:217], v[20:23]
	v_mfma_f32_16x16x32_bf16 v[16:19], v[180:183], v[214:217], v[16:19]
	v_mfma_f32_16x16x32_bf16 v[4:7], v[148:151], v[222:225], v[4:7]
	v_mfma_f32_16x16x32_bf16 v[0:3], v[180:183], v[222:225], v[0:3]
	s_barrier
	s_setprio 0
	s_cbranch_scc0 .LBB0_146
	s_and_b64 vcc, exec, s[18:19]
	s_cbranch_vccz .LBB0_149
	s_barrier

.LBB0_250:
	ds_read_b128 v[148:151], v142
	ds_read_b128 v[152:155], v142 offset:1024
	ds_read_b128 v[156:159], v142 offset:2048
	ds_read_b128 v[160:163], v142 offset:3072
	ds_read_b128 v[164:167], v143
	ds_read_b128 v[168:171], v143 offset:1024
	ds_read_b128 v[176:179], v143 offset:2048
	ds_read_b128 v[180:183], v143 offset:3072
	s_add_i32 s20, s18, 0xf4f60080
	s_cmp_lg_u32 s52, 28
	s_cselect_b32 s20, s20, 0
	s_add_u32 s22, s2, s20
	s_addc_u32 s23, s3, 0
	s_add_u32 s20, s12, s20
	s_addc_u32 s21, s13, 0
	s_mov_b32 m0, s53
	v_lshl_add_u64 v[172:173], v[138:139], 0, s[18:19]
	ds_read_b128 v[188:191], v144
	ds_read_b128 v[192:195], v144 offset:1024
	ds_read_b128 v[196:199], v144 offset:2048
	ds_read_b128 v[200:203], v144 offset:3072
	ds_read_b128 v[204:207], v144 offset:4096
	ds_read_b128 v[208:211], v144 offset:5120
	ds_read_b128 v[212:215], v144 offset:6144
	ds_read_b128 v[216:219], v144 offset:7168
	global_load_lds_dwordx4 v[172:173], off
	v_lshl_add_u64 v[172:173], v[140:141], 0, s[18:19]
	s_mov_b32 m0, s54
	s_nop 0
	global_load_lds_dwordx4 v[172:173], off
	s_waitcnt vmcnt(8) lgkmcnt(0)
	s_setprio 1
	s_barrier
	v_mfma_f32_16x16x32_bf16 v[124:127], v[148:151], v[188:191], v[124:127]
	v_mfma_f32_16x16x32_bf16 v[120:123], v[156:159], v[188:191], v[120:123]
	v_mfma_f32_16x16x32_bf16 v[116:119], v[148:151], v[196:199], v[116:119]
	v_mfma_f32_16x16x32_bf16 v[112:115], v[156:159], v[196:199], v[112:115]
	v_mfma_f32_16x16x32_bf16 v[100:103], v[148:151], v[204:207], v[100:103]
	v_mfma_f32_16x16x32_bf16 v[96:99], v[156:159], v[204:207], v[96:99]
	v_mfma_f32_16x16x32_bf16 v[84:87], v[148:151], v[212:215], v[84:87]
	v_mfma_f32_16x16x32_bf16 v[80:83], v[156:159], v[212:215], v[80:83]
	v_mfma_f32_16x16x32_bf16 v[124:127], v[152:155], v[192:195], v[124:127]
	v_mfma_f32_16x16x32_bf16 v[120:123], v[160:163], v[192:195], v[120:123]
	v_mfma_f32_16x16x32_bf16 v[116:119], v[152:155], v[200:203], v[116:119]
	v_mfma_f32_16x16x32_bf16 v[112:115], v[160:163], v[200:203], v[112:115]
	v_mfma_f32_16x16x32_bf16 v[100:103], v[152:155], v[208:211], v[100:103]
	v_mfma_f32_16x16x32_bf16 v[96:99], v[160:163], v[208:211], v[96:99]
	v_mfma_f32_16x16x32_bf16 v[84:87], v[152:155], v[216:219], v[84:87]
	v_mfma_f32_16x16x32_bf16 v[80:83], v[160:163], v[216:219], v[80:83]
	s_setprio 0
	s_setprio 1
	v_mfma_f32_16x16x32_bf16 v[108:111], v[164:167], v[188:191], v[108:111]
	v_mfma_f32_16x16x32_bf16 v[104:107], v[176:179], v[188:191], v[104:107]
	v_mfma_f32_16x16x32_bf16 v[92:95], v[164:167], v[196:199], v[92:95]
	v_mfma_f32_16x16x32_bf16 v[88:91], v[176:179], v[196:199], v[88:91]
	v_mfma_f32_16x16x32_bf16 v[76:79], v[164:167], v[204:207], v[76:79]
	v_mfma_f32_16x16x32_bf16 v[72:75], v[176:179], v[204:207], v[72:75]
	v_mfma_f32_16x16x32_bf16 v[68:71], v[164:167], v[212:215], v[68:71]
	v_mfma_f32_16x16x32_bf16 v[64:67], v[176:179], v[212:215], v[64:67]
	v_mfma_f32_16x16x32_bf16 v[108:111], v[168:171], v[192:195], v[108:111]
	v_mfma_f32_16x16x32_bf16 v[104:107], v[180:183], v[192:195], v[104:107]
	v_mfma_f32_16x16x32_bf16 v[92:95], v[168:171], v[200:203], v[92:95]
	v_mfma_f32_16x16x32_bf16 v[88:91], v[180:183], v[200:203], v[88:91]
	v_mfma_f32_16x16x32_bf16 v[76:79], v[168:171], v[208:211], v[76:79]
	v_mfma_f32_16x16x32_bf16 v[72:75], v[180:183], v[208:211], v[72:75]
	v_mfma_f32_16x16x32_bf16 v[68:71], v[168:171], v[216:219], v[68:71]
	v_mfma_f32_16x16x32_bf16 v[64:67], v[180:183], v[216:219], v[64:67]
	s_barrier
	s_setprio 0
	s_mov_b32 m0, s55
	v_lshl_add_u64 v[172:173], s[20:21], 0, v[132:133]
	s_add_u32 s64, s20, 0x80000
	ds_read_b128 v[188:191], v144 offset:16384
	ds_read_b128 v[192:195], v144 offset:17408
	ds_read_b128 v[196:199], v144 offset:18432
	ds_read_b128 v[200:203], v144 offset:19456
	ds_read_b128 v[204:207], v144 offset:20480
	ds_read_b128 v[208:211], v144 offset:21504
	ds_read_b128 v[212:215], v144 offset:22528
	ds_read_b128 v[216:219], v144 offset:23552
	global_load_lds_dwordx4 v[172:173], off
	v_lshl_add_u64 v[184:185], s[20:21], 0, v[128:129]
	s_mov_b32 m0, s56
	s_addc_u32 s65, s21, 0
	global_load_lds_dwordx4 v[184:185], off
	v_lshl_add_u64 v[220:221], s[64:65], 0, v[132:133]
	s_mov_b32 m0, s57
	v_lshl_add_u64 v[222:223], s[22:23], 0, v[130:131]
	global_load_lds_dwordx4 v[220:221], off
	s_mov_b32 m0, s58
	v_lshl_add_u64 v[220:221], s[64:65], 0, v[128:129]
	global_load_lds_dwordx4 v[220:221], off
	s_mov_b32 m0, s1
	v_lshl_add_u64 v[220:221], s[22:23], 0, v[134:135]
	global_load_lds_dwordx4 v[220:221], off
	s_mov_b32 m0, s26
	s_nop 0
	global_load_lds_dwordx4 v[222:223], off
	s_waitcnt vmcnt(8) lgkmcnt(0)
	s_setprio 1
	s_barrier
	v_mfma_f32_16x16x32_bf16 v[60:63], v[148:151], v[188:191], v[60:63]
	v_mfma_f32_16x16x32_bf16 v[56:59], v[156:159], v[188:191], v[56:59]
	v_mfma_f32_16x16x32_bf16 v[52:55], v[148:151], v[196:199], v[52:55]
	v_mfma_f32_16x16x32_bf16 v[48:51], v[156:159], v[196:199], v[48:51]
	v_mfma_f32_16x16x32_bf16 v[36:39], v[148:151], v[204:207], v[36:39]
	v_mfma_f32_16x16x32_bf16 v[32:35], v[156:159], v[204:207], v[32:35]
	v_mfma_f32_16x16x32_bf16 v[20:23], v[148:151], v[212:215], v[20:23]
	v_mfma_f32_16x16x32_bf16 v[16:19], v[156:159], v[212:215], v[16:19]
	v_mfma_f32_16x16x32_bf16 v[60:63], v[152:155], v[192:195], v[60:63]
	v_mfma_f32_16x16x32_bf16 v[56:59], v[160:163], v[192:195], v[56:59]
	v_mfma_f32_16x16x32_bf16 v[52:55], v[152:155], v[200:203], v[52:55]
	v_mfma_f32_16x16x32_bf16 v[48:51], v[160:163], v[200:203], v[48:51]
	v_mfma_f32_16x16x32_bf16 v[36:39], v[152:155], v[208:211], v[36:39]
	v_mfma_f32_16x16x32_bf16 v[32:35], v[160:163], v[208:211], v[32:35]
	v_mfma_f32_16x16x32_bf16 v[20:23], v[152:155], v[216:219], v[20:23]
	v_mfma_f32_16x16x32_bf16 v[16:19], v[160:163], v[216:219], v[16:19]
	s_setprio 0
	s_setprio 1
	v_mfma_f32_16x16x32_bf16 v[44:47], v[164:167], v[188:191], v[44:47]
	v_mfma_f32_16x16x32_bf16 v[40:43], v[176:179], v[188:191], v[40:43]
	v_mfma_f32_16x16x32_bf16 v[28:31], v[164:167], v[196:199], v[28:31]
	v_mfma_f32_16x16x32_bf16 v[24:27], v[176:179], v[196:199], v[24:27]
	v_mfma_f32_16x16x32_bf16 v[12:15], v[164:167], v[204:207], v[12:15]
	v_mfma_f32_16x16x32_bf16 v[8:11], v[176:179], v[204:207], v[8:11]
	v_mfma_f32_16x16x32_bf16 v[4:7], v[164:167], v[212:215], v[4:7]
	v_mfma_f32_16x16x32_bf16 v[0:3], v[176:179], v[212:215], v[0:3]
	v_mfma_f32_16x16x32_bf16 v[44:47], v[168:171], v[192:195], v[44:47]
	v_mfma_f32_16x16x32_bf16 v[40:43], v[180:183], v[192:195], v[40:43]
	v_mfma_f32_16x16x32_bf16 v[28:31], v[168:171], v[200:203], v[28:31]
	v_mfma_f32_16x16x32_bf16 v[24:27], v[180:183], v[200:203], v[24:27]
	v_mfma_f32_16x16x32_bf16 v[12:15], v[168:171], v[208:211], v[12:15]
	v_mfma_f32_16x16x32_bf16 v[8:11], v[180:183], v[208:211], v[8:11]
	v_mfma_f32_16x16x32_bf16 v[4:7], v[168:171], v[216:219], v[4:7]
	v_mfma_f32_16x16x32_bf16 v[0:3], v[180:183], v[216:219], v[0:3]
	s_barrier
	s_setprio 0
	ds_read_b128 v[148:151], v145
	ds_read_b128 v[152:155], v145 offset:1024
	ds_read_b128 v[156:159], v145 offset:2048
	ds_read_b128 v[160:163], v145 offset:3072
	ds_read_b128 v[164:167], v146
	ds_read_b128 v[168:171], v146 offset:1024
	ds_read_b128 v[176:179], v146 offset:2048
	ds_read_b128 v[180:183], v146 offset:3072
	s_add_u32 s22, s22, 0xa0000
	s_addc_u32 s23, s23, 0
	s_mov_b32 m0, s27
	v_lshl_add_u64 v[224:225], s[22:23], 0, v[134:135]
	ds_read_b128 v[188:191], v144 offset:32768
	ds_read_b128 v[192:195], v144 offset:33792
	ds_read_b128 v[196:199], v144 offset:34816
	ds_read_b128 v[200:203], v144 offset:35840
	ds_read_b128 v[204:207], v144 offset:36864
	ds_read_b128 v[208:211], v144 offset:37888
	ds_read_b128 v[212:215], v144 offset:38912
	ds_read_b128 v[216:219], v144 offset:39936
	global_load_lds_dwordx4 v[224:225], off
	v_lshl_add_u64 v[224:225], s[22:23], 0, v[130:131]
	s_mov_b32 m0, s48
	s_nop 0
	global_load_lds_dwordx4 v[224:225], off
	s_waitcnt vmcnt(8) lgkmcnt(0)
	s_setprio 1
	s_barrier
	v_mfma_f32_16x16x32_bf16 v[124:127], v[148:151], v[188:191], v[124:127]
	v_mfma_f32_16x16x32_bf16 v[120:123], v[156:159], v[188:191], v[120:123]
	v_mfma_f32_16x16x32_bf16 v[116:119], v[148:151], v[196:199], v[116:119]
	v_mfma_f32_16x16x32_bf16 v[112:115], v[156:159], v[196:199], v[112:115]
	v_mfma_f32_16x16x32_bf16 v[100:103], v[148:151], v[204:207], v[100:103]
	v_mfma_f32_16x16x32_bf16 v[96:99], v[156:159], v[204:207], v[96:99]
	v_mfma_f32_16x16x32_bf16 v[84:87], v[148:151], v[212:215], v[84:87]
	v_mfma_f32_16x16x32_bf16 v[80:83], v[156:159], v[212:215], v[80:83]
	v_mfma_f32_16x16x32_bf16 v[124:127], v[152:155], v[192:195], v[124:127]
	v_mfma_f32_16x16x32_bf16 v[120:123], v[160:163], v[192:195], v[120:123]
	v_mfma_f32_16x16x32_bf16 v[116:119], v[152:155], v[200:203], v[116:119]
	v_mfma_f32_16x16x32_bf16 v[112:115], v[160:163], v[200:203], v[112:115]
	v_mfma_f32_16x16x32_bf16 v[100:103], v[152:155], v[208:211], v[100:103]
	v_mfma_f32_16x16x32_bf16 v[96:99], v[160:163], v[208:211], v[96:99]
	v_mfma_f32_16x16x32_bf16 v[84:87], v[152:155], v[216:219], v[84:87]
	v_mfma_f32_16x16x32_bf16 v[80:83], v[160:163], v[216:219], v[80:83]
	s_setprio 0
	s_setprio 1
	v_mfma_f32_16x16x32_bf16 v[108:111], v[164:167], v[188:191], v[108:111]
	v_mfma_f32_16x16x32_bf16 v[104:107], v[176:179], v[188:191], v[104:107]
	v_mfma_f32_16x16x32_bf16 v[92:95], v[164:167], v[196:199], v[92:95]
	v_mfma_f32_16x16x32_bf16 v[88:91], v[176:179], v[196:199], v[88:91]
	v_mfma_f32_16x16x32_bf16 v[76:79], v[164:167], v[204:207], v[76:79]
	v_mfma_f32_16x16x32_bf16 v[72:75], v[176:179], v[204:207], v[72:75]
	v_mfma_f32_16x16x32_bf16 v[68:71], v[164:167], v[212:215], v[68:71]
	v_mfma_f32_16x16x32_bf16 v[64:67], v[176:179], v[212:215], v[64:67]
	v_mfma_f32_16x16x32_bf16 v[108:111], v[168:171], v[192:195], v[108:111]
	v_mfma_f32_16x16x32_bf16 v[104:107], v[180:183], v[192:195], v[104:107]
	v_mfma_f32_16x16x32_bf16 v[92:95], v[168:171], v[200:203], v[92:95]
	v_mfma_f32_16x16x32_bf16 v[88:91], v[180:183], v[200:203], v[88:91]
	v_mfma_f32_16x16x32_bf16 v[76:79], v[168:171], v[208:211], v[76:79]
	v_mfma_f32_16x16x32_bf16 v[72:75], v[180:183], v[208:211], v[72:75]
	v_mfma_f32_16x16x32_bf16 v[68:71], v[168:171], v[216:219], v[68:71]
	v_mfma_f32_16x16x32_bf16 v[64:67], v[180:183], v[216:219], v[64:67]
	s_barrier
	s_setprio 0
	s_mov_b32 m0, s59
	v_lshl_add_u64 v[172:173], v[172:173], 0, s[14:15]
	s_add_u32 s20, s20, 0x80080
	ds_read_b128 v[188:191], v144 offset:49152
	ds_read_b128 v[192:195], v144 offset:50176
	ds_read_b128 v[196:199], v144 offset:51200
	ds_read_b128 v[200:203], v144 offset:52224
	ds_read_b128 v[204:207], v144 offset:53248
	ds_read_b128 v[208:211], v144 offset:54272
	ds_read_b128 v[212:215], v144 offset:55296
	ds_read_b128 v[216:219], v144 offset:56320
	global_load_lds_dwordx4 v[172:173], off
	v_lshl_add_u64 v[172:173], v[184:185], 0, s[14:15]
	s_mov_b32 m0, s60
	s_addc_u32 s21, s21, 0
	global_load_lds_dwordx4 v[172:173], off
	s_mov_b32 m0, s61
	v_lshl_add_u64 v[172:173], s[20:21], 0, v[132:133]
	global_load_lds_dwordx4 v[172:173], off
	s_mov_b32 m0, s62
	v_lshl_add_u64 v[172:173], s[20:21], 0, v[128:129]
	global_load_lds_dwordx4 v[172:173], off
	s_mov_b32 m0, s50
	v_lshl_add_u64 v[172:173], v[220:221], 0, s[14:15]
	global_load_lds_dwordx4 v[172:173], off
	s_mov_b32 m0, s51
	v_lshl_add_u64 v[172:173], v[222:223], 0, s[14:15]
	global_load_lds_dwordx4 v[172:173], off
	s_waitcnt vmcnt(8) lgkmcnt(0)
	s_setprio 1
	s_barrier
	v_mfma_f32_16x16x32_bf16 v[60:63], v[148:151], v[188:191], v[60:63]
	v_mfma_f32_16x16x32_bf16 v[56:59], v[156:159], v[188:191], v[56:59]
	v_mfma_f32_16x16x32_bf16 v[52:55], v[148:151], v[196:199], v[52:55]
	v_mfma_f32_16x16x32_bf16 v[48:51], v[156:159], v[196:199], v[48:51]
	v_mfma_f32_16x16x32_bf16 v[36:39], v[148:151], v[204:207], v[36:39]
	v_mfma_f32_16x16x32_bf16 v[32:35], v[156:159], v[204:207], v[32:35]
	v_mfma_f32_16x16x32_bf16 v[20:23], v[148:151], v[212:215], v[20:23]
	v_mfma_f32_16x16x32_bf16 v[16:19], v[156:159], v[212:215], v[16:19]
	v_mfma_f32_16x16x32_bf16 v[60:63], v[152:155], v[192:195], v[60:63]
	v_mfma_f32_16x16x32_bf16 v[56:59], v[160:163], v[192:195], v[56:59]
	v_mfma_f32_16x16x32_bf16 v[52:55], v[152:155], v[200:203], v[52:55]
	v_mfma_f32_16x16x32_bf16 v[48:51], v[160:163], v[200:203], v[48:51]
	v_mfma_f32_16x16x32_bf16 v[36:39], v[152:155], v[208:211], v[36:39]
	v_mfma_f32_16x16x32_bf16 v[32:35], v[160:163], v[208:211], v[32:35]
	v_mfma_f32_16x16x32_bf16 v[20:23], v[152:155], v[216:219], v[20:23]
	v_mfma_f32_16x16x32_bf16 v[16:19], v[160:163], v[216:219], v[16:19]
	s_setprio 0
	s_setprio 1
	v_mfma_f32_16x16x32_bf16 v[44:47], v[164:167], v[188:191], v[44:47]
	v_mfma_f32_16x16x32_bf16 v[40:43], v[176:179], v[188:191], v[40:43]
	v_mfma_f32_16x16x32_bf16 v[28:31], v[164:167], v[196:199], v[28:31]
	v_mfma_f32_16x16x32_bf16 v[24:27], v[176:179], v[196:199], v[24:27]
	v_mfma_f32_16x16x32_bf16 v[12:15], v[164:167], v[204:207], v[12:15]
	v_mfma_f32_16x16x32_bf16 v[8:11], v[176:179], v[204:207], v[8:11]
	v_mfma_f32_16x16x32_bf16 v[4:7], v[164:167], v[212:215], v[4:7]
	v_mfma_f32_16x16x32_bf16 v[0:3], v[176:179], v[212:215], v[0:3]
	v_mfma_f32_16x16x32_bf16 v[44:47], v[168:171], v[192:195], v[44:47]
	v_mfma_f32_16x16x32_bf16 v[40:43], v[180:183], v[192:195], v[40:43]
	v_mfma_f32_16x16x32_bf16 v[28:31], v[168:171], v[200:203], v[28:31]
	v_mfma_f32_16x16x32_bf16 v[24:27], v[180:183], v[200:203], v[24:27]
	v_mfma_f32_16x16x32_bf16 v[12:15], v[168:171], v[208:211], v[12:15]
	v_mfma_f32_16x16x32_bf16 v[8:11], v[180:183], v[208:211], v[8:11]
	v_mfma_f32_16x16x32_bf16 v[4:7], v[168:171], v[216:219], v[4:7]
	v_mfma_f32_16x16x32_bf16 v[0:3], v[180:183], v[216:219], v[0:3]
	s_barrier
	s_setprio 0
	s_add_i32 s52, s52, 2
	s_add_u32 s18, s18, 0x100
	s_addc_u32 s19, s19, 0
	s_cmp_gt_u32 s52, 29
	s_cbranch_scc0 .LBB0_250
	s_cmpk_lt_u32 s24, 0x100
	s_cbranch_scc0 .LBB0_253
	s_barrier

.LBB0_261:
	s_or_b64 exec, exec, s[0:1]
	s_add_u32 s12, s38, 0x500000
	s_addc_u32 s13, s39, 0
	s_add_u32 s14, s38, 0xbb62c00
	s_addc_u32 s15, s39, 0
	s_add_u32 s18, s38, 0xbb63800
	s_addc_u32 s19, s39, 0
	s_add_i32 s27, 0, 0x22000
	s_mov_b64 s[22:23], 0
	s_mov_b32 s21, 0
	v_mov_b32_e32 v173, s27
	v_mov_b32_e32 v1, 0
	s_movk_i32 s62, 0x5800
	s_mov_b64 s[24:25], 0x800
	s_movk_i32 s63, 0x1ff
	s_add_i32 s64, 0, 0x20000
	s_movk_i32 s65, 0x1000
	s_mov_b32 s26, 0x3b800000
	s_add_i32 s97, 0, 0x20800
	s_mov_b32 s67, 0xf149f2ca
	s_mov_b32 s68, 0xffff0000
	s_movk_i32 s69, 0x50
	s_movk_i32 s70, 0x60
	s_movk_i32 s71, 0x70
	s_movk_i32 s72, 0x80
	s_movk_i32 s73, 0x90
	s_movk_i32 s79, 0xa0
	s_movk_i32 s80, 0xb0
	s_movk_i32 s81, 0xc0
	s_movk_i32 s82, 0xd0
	s_movk_i32 s83, 0xe0
	s_movk_i32 s84, 0xf0
	s_movk_i32 s85, 0x1400
	s_movk_i32 s86, 0x5000
	s_mov_b64 s[48:49], 0xa000
	s_movk_i32 s87, 0x210
	s_movk_i32 s88, 0x81
	s_mov_b64 s[50:51], 0x160000
	v_mov_b32_e32 v188, 0x16000
	v_mov_b32_e32 v189, 0x2c000
	v_mov_b32_e32 v190, 0x42000
	v_mov_b32_e32 v191, 0x58000
	v_mov_b32_e32 v192, 0x6e000
	v_mov_b32_e32 v193, 0x84000
	v_mov_b32_e32 v194, 0x9a000
	v_mov_b32_e32 v195, 0xf149f2ca
	v_mov_b32_e32 v196, 0x14000
	v_mov_b32_e32 v197, 0x19000
	v_mov_b32_e32 v198, 0x1e000
	v_mov_b32_e32 v199, 0x23000
	v_writelane_b32 v244, s97, 2
	s_branch .LBB0_265
	s_nop 0
	s_nop 0
	s_nop 0
	s_nop 0
	s_nop 0
	s_nop 0
	s_nop 0
	s_nop 0
	s_nop 0
	s_nop 0
	s_nop 0
	s_nop 0

.Lpeel_mid_p3:
	s_add_i32 s75, 0, 0x18000
	v_add_u32_e32 v1, s75, v173
	s_add_i32 s91, 0, 0x1c000
	ds_read_b128 v[132:135], v1
	ds_read_b128 v[136:139], v1 offset:1024
	ds_read_b128 v[140:143], v1 offset:2048
	ds_read_b128 v[178:181], v1 offset:3072
	v_add_u32_e32 v1, s91, v173
	ds_read_b128 v[182:185], v1
	ds_read_b128 v[188:191], v1 offset:1024
	ds_read_b128 v[192:195], v1 offset:2048
	ds_read_b128 v[196:199], v1 offset:3072
	s_add_u32 s66, s66, 0xa0000
	s_addc_u32 s67, s67, 0
	s_mov_b32 m0, s71
	v_lshl_add_u64 v[6:7], s[66:67], 0, v[150:151]
	ds_read_b128 v[200:203], v174 offset:32768
	ds_read_b128 v[204:207], v174 offset:33792
	ds_read_b128 v[208:211], v174 offset:34816
	ds_read_b128 v[212:215], v174 offset:35840
	ds_read_b128 v[216:219], v174 offset:36864
	ds_read_b128 v[220:223], v174 offset:37888
	ds_read_b128 v[224:227], v174 offset:38912
	ds_read_b128 v[228:231], v174 offset:39936
	global_load_lds_dwordx4 v[6:7], off
	v_lshl_add_u64 v[6:7], s[66:67], 0, v[146:147]
	s_mov_b32 m0, s72
	s_nop 0
	global_load_lds_dwordx4 v[6:7], off
	s_waitcnt vmcnt(8) lgkmcnt(0)
	s_setprio 1
	s_barrier
	v_mfma_f32_16x16x32_bf16 v[128:131], v[132:135], v[200:203], v[128:131]
	v_mfma_f32_16x16x32_bf16 v[124:127], v[140:143], v[200:203], v[124:127]
	v_mfma_f32_16x16x32_bf16 v[112:115], v[132:135], v[208:211], v[112:115]
	v_mfma_f32_16x16x32_bf16 v[108:111], v[140:143], v[208:211], v[108:111]
	v_mfma_f32_16x16x32_bf16 v[96:99], v[132:135], v[216:219], v[96:99]
	v_mfma_f32_16x16x32_bf16 v[92:95], v[140:143], v[216:219], v[92:95]
	v_mfma_f32_16x16x32_bf16 v[80:83], v[132:135], v[224:227], v[80:83]
	v_mfma_f32_16x16x32_bf16 v[76:79], v[140:143], v[224:227], v[76:79]
	v_mfma_f32_16x16x32_bf16 v[128:131], v[136:139], v[204:207], v[128:131]
	v_mfma_f32_16x16x32_bf16 v[124:127], v[178:181], v[204:207], v[124:127]
	v_mfma_f32_16x16x32_bf16 v[112:115], v[136:139], v[212:215], v[112:115]
	v_mfma_f32_16x16x32_bf16 v[108:111], v[178:181], v[212:215], v[108:111]
	v_mfma_f32_16x16x32_bf16 v[96:99], v[136:139], v[220:223], v[96:99]
	v_mfma_f32_16x16x32_bf16 v[92:95], v[178:181], v[220:223], v[92:95]
	v_mfma_f32_16x16x32_bf16 v[80:83], v[136:139], v[228:231], v[80:83]
	v_mfma_f32_16x16x32_bf16 v[76:79], v[178:181], v[228:231], v[76:79]
	s_setprio 0
	s_setprio 1
	v_mfma_f32_16x16x32_bf16 v[120:123], v[182:185], v[200:203], v[120:123]
	v_mfma_f32_16x16x32_bf16 v[116:119], v[192:195], v[200:203], v[116:119]
	v_mfma_f32_16x16x32_bf16 v[104:107], v[182:185], v[208:211], v[104:107]
	v_mfma_f32_16x16x32_bf16 v[100:103], v[192:195], v[208:211], v[100:103]
	v_mfma_f32_16x16x32_bf16 v[88:91], v[182:185], v[216:219], v[88:91]
	v_mfma_f32_16x16x32_bf16 v[84:87], v[192:195], v[216:219], v[84:87]
	v_mfma_f32_16x16x32_bf16 v[72:75], v[182:185], v[224:227], v[72:75]
	v_mfma_f32_16x16x32_bf16 v[68:71], v[192:195], v[224:227], v[68:71]
	v_mfma_f32_16x16x32_bf16 v[120:123], v[188:191], v[204:207], v[120:123]
	v_mfma_f32_16x16x32_bf16 v[116:119], v[196:199], v[204:207], v[116:119]
	v_mfma_f32_16x16x32_bf16 v[104:107], v[188:191], v[212:215], v[104:107]
	v_mfma_f32_16x16x32_bf16 v[100:103], v[196:199], v[212:215], v[100:103]
	v_mfma_f32_16x16x32_bf16 v[88:91], v[188:191], v[220:223], v[88:91]
	v_mfma_f32_16x16x32_bf16 v[84:87], v[196:199], v[220:223], v[84:87]
	v_mfma_f32_16x16x32_bf16 v[72:75], v[188:191], v[228:231], v[72:75]
	v_mfma_f32_16x16x32_bf16 v[68:71], v[196:199], v[228:231], v[68:71]
	s_barrier
	s_setprio 0
	s_add_i32 s66, s75, s68
	v_lshl_add_u64 v[6:7], v[232:233], 0, s[14:15]
	s_mov_b32 m0, s66
	ds_read_b128 v[200:203], v174 offset:49152
	ds_read_b128 v[204:207], v174 offset:50176
	ds_read_b128 v[208:211], v174 offset:51200
	ds_read_b128 v[212:215], v174 offset:52224
	ds_read_b128 v[216:219], v174 offset:53248
	ds_read_b128 v[220:223], v174 offset:54272
	ds_read_b128 v[224:227], v174 offset:55296
	ds_read_b128 v[228:231], v174 offset:56320
	global_load_lds_dwordx4 v[6:7], off
	s_add_i32 m0, s66, 0x2000
	s_add_u32 s64, s64, 0xa0080
	v_lshl_add_u64 v[6:7], v[234:235], 0, s[14:15]
	s_addc_u32 s65, s65, 0
	s_add_i32 s66, s91, s68
	global_load_lds_dwordx4 v[6:7], off
	s_mov_b32 m0, s66
	v_lshl_add_u64 v[6:7], s[64:65], 0, v[148:149]
	global_load_lds_dwordx4 v[6:7], off
	s_add_i32 m0, s66, 0x2000
	v_lshl_add_u64 v[6:7], s[64:65], 0, v[144:145]
	global_load_lds_dwordx4 v[6:7], off
	s_mov_b32 m0, s73
	v_lshl_add_u64 v[6:7], v[236:237], 0, s[14:15]
	global_load_lds_dwordx4 v[6:7], off
	s_mov_b32 m0, s76
	v_lshl_add_u64 v[6:7], v[238:239], 0, s[14:15]
	global_load_lds_dwordx4 v[6:7], off
	s_waitcnt vmcnt(8) lgkmcnt(0)
	s_setprio 1
	s_barrier
	v_mfma_f32_16x16x32_bf16 v[64:67], v[132:135], v[200:203], v[64:67]
	v_mfma_f32_16x16x32_bf16 v[60:63], v[140:143], v[200:203], v[60:63]
	v_mfma_f32_16x16x32_bf16 v[48:51], v[132:135], v[208:211], v[48:51]
	v_mfma_f32_16x16x32_bf16 v[44:47], v[140:143], v[208:211], v[44:47]
	v_mfma_f32_16x16x32_bf16 v[32:35], v[132:135], v[216:219], v[32:35]
	v_mfma_f32_16x16x32_bf16 v[28:31], v[140:143], v[216:219], v[28:31]
	v_mfma_f32_16x16x32_bf16 v[16:19], v[132:135], v[224:227], v[16:19]
	v_mfma_f32_16x16x32_bf16 v[12:15], v[140:143], v[224:227], v[12:15]
	v_mfma_f32_16x16x32_bf16 v[64:67], v[136:139], v[204:207], v[64:67]
	v_mfma_f32_16x16x32_bf16 v[60:63], v[178:181], v[204:207], v[60:63]
	v_mfma_f32_16x16x32_bf16 v[48:51], v[136:139], v[212:215], v[48:51]
	s_add_u32 s60, s60, 0x100
	v_mfma_f32_16x16x32_bf16 v[44:47], v[178:181], v[212:215], v[44:47]
	s_addc_u32 s61, s61, 0
	v_mfma_f32_16x16x32_bf16 v[32:35], v[136:139], v[220:223], v[32:35]
	s_cmp_eq_u32 s2, 16
	v_mfma_f32_16x16x32_bf16 v[28:31], v[178:181], v[220:223], v[28:31]
	s_cselect_b32 s100, 1, 0
	v_mfma_f32_16x16x32_bf16 v[16:19], v[136:139], v[228:231], v[16:19]
	s_cmp_eq_u32 s2, 24
	v_mfma_f32_16x16x32_bf16 v[12:15], v[178:181], v[228:231], v[12:15]
	s_cselect_b32 s101, 1, 0
	s_setprio 0
	s_setprio 1
	v_mfma_f32_16x16x32_bf16 v[56:59], v[182:185], v[200:203], v[56:59]
	s_or_b32 s100, s100, s101
	v_mfma_f32_16x16x32_bf16 v[52:55], v[192:195], v[200:203], v[52:55]
	s_cmp_eq_u64 s[62:63], 0
	v_mfma_f32_16x16x32_bf16 v[40:43], v[182:185], v[208:211], v[40:43]
	s_cselect_b32 s100, s100, 0
	v_mfma_f32_16x16x32_bf16 v[36:39], v[192:195], v[208:211], v[36:39]
	s_cmp_ge_i32 s2, s88
	v_mfma_f32_16x16x32_bf16 v[24:27], v[182:185], v[216:219], v[24:27]
	s_cselect_b32 s67, 1, 0
	v_mfma_f32_16x16x32_bf16 v[20:23], v[192:195], v[216:219], v[20:23]
	s_cmp_eq_u64 s[18:19], 0
	v_mfma_f32_16x16x32_bf16 v[6:9], v[182:185], v[224:227], v[8:11]
	s_cselect_b32 s66, 0, s100
	v_mfma_f32_16x16x32_bf16 v[2:5], v[192:195], v[224:227], v[2:5]
	s_cselect_b32 s100, s100, 0
	v_mfma_f32_16x16x32_bf16 v[56:59], v[188:191], v[204:207], v[56:59]
	s_or_b32 s66, s66, s67
	v_mfma_f32_16x16x32_bf16 v[52:55], v[196:199], v[204:207], v[52:55]
	s_mov_b32 s64, s2
	v_mfma_f32_16x16x32_bf16 v[40:43], v[188:191], v[212:215], v[40:43]
	s_cmp_lg_u32 s100, 0
	v_mfma_f32_16x16x32_bf16 v[36:39], v[196:199], v[212:215], v[36:39]
	v_mfma_f32_16x16x32_bf16 v[24:27], v[188:191], v[220:223], v[24:27]
	v_mfma_f32_16x16x32_bf16 v[20:23], v[196:199], v[220:223], v[20:23]
	v_mfma_f32_16x16x32_bf16 v[8:11], v[188:191], v[228:231], v[6:9]
	v_mfma_f32_16x16x32_bf16 v[4:7], v[196:199], v[228:231], v[2:5]
	s_setprio 0
	s_cbranch_scc0 .Lhk_skipB

.LBB0_671:
	s_add_u32 s6, s6, 0x80080
	s_addc_u32 s7, s7, 0
	s_add_u32 s5, s40, 0x100
	s_addc_u32 s25, s41, 0
	s_mov_b32 s56, -2
	ds_read_b128 v[128:131], v185
	ds_read_b128 v[132:135], v185 offset:1024
	ds_read_b128 v[136:139], v185 offset:2048
	ds_read_b128 v[140:143], v185 offset:3072
	ds_read_b128 v[162:165], v186
	ds_read_b128 v[166:169], v186 offset:1024
	ds_read_b128 v[170:173], v186 offset:2048
	ds_read_b128 v[174:177], v186 offset:3072
	s_add_u32 s38, s6, 0xfff80080
	s_addc_u32 s39, s7, -1
	s_cmp_eq_u32 s56, 28
	s_cselect_b32 s41, s27, s39
	s_cselect_b32 s40, s26, s38
	s_cselect_b32 s39, s23, s25
	s_cselect_b32 s38, s22, s5
	v_lshl_add_u64 v[182:183], s[6:7], 0, v[158:159]
	s_add_i32 m0, s42, 0xc000
	ds_read_b128 v[178:181], v188
	ds_read_b128 v[192:195], v188 offset:1024
	ds_read_b128 v[196:199], v188 offset:2048
	ds_read_b128 v[200:203], v188 offset:3072
	ds_read_b128 v[204:207], v188 offset:4096
	ds_read_b128 v[208:211], v188 offset:5120
	ds_read_b128 v[212:215], v188 offset:6144
	ds_read_b128 v[216:219], v188 offset:7168
	global_load_lds_dwordx4 v[182:183], off
	v_lshl_add_u64 v[182:183], s[6:7], 0, v[160:161]
	s_add_i32 m0, s42, 0xe000
	s_nop 0
	global_load_lds_dwordx4 v[182:183], off
	s_waitcnt vmcnt(8) lgkmcnt(0)
	s_setprio 1
	s_barrier
	v_mfma_f32_16x16x32_bf16 v[124:127], v[128:131], v[178:181], 0
	v_mfma_f32_16x16x32_bf16 v[120:123], v[136:139], v[178:181], 0
	v_mfma_f32_16x16x32_bf16 v[108:111], v[128:131], v[196:199], 0
	v_mfma_f32_16x16x32_bf16 v[104:107], v[136:139], v[196:199], 0
	v_mfma_f32_16x16x32_bf16 v[92:95], v[128:131], v[204:207], 0
	v_mfma_f32_16x16x32_bf16 v[88:91], v[136:139], v[204:207], 0
	v_mfma_f32_16x16x32_bf16 v[76:79], v[128:131], v[212:215], 0
	v_mfma_f32_16x16x32_bf16 v[72:75], v[136:139], v[212:215], 0
	v_mfma_f32_16x16x32_bf16 v[124:127], v[132:135], v[192:195], v[124:127]
	v_mfma_f32_16x16x32_bf16 v[120:123], v[140:143], v[192:195], v[120:123]
	v_mfma_f32_16x16x32_bf16 v[108:111], v[132:135], v[200:203], v[108:111]
	v_mfma_f32_16x16x32_bf16 v[104:107], v[140:143], v[200:203], v[104:107]
	v_mfma_f32_16x16x32_bf16 v[92:95], v[132:135], v[208:211], v[92:95]
	v_mfma_f32_16x16x32_bf16 v[88:91], v[140:143], v[208:211], v[88:91]
	v_mfma_f32_16x16x32_bf16 v[76:79], v[132:135], v[216:219], v[76:79]
	v_mfma_f32_16x16x32_bf16 v[72:75], v[140:143], v[216:219], v[72:75]
	s_setprio 0
	s_setprio 1
	v_mfma_f32_16x16x32_bf16 v[116:119], v[162:165], v[178:181], 0
	v_mfma_f32_16x16x32_bf16 v[112:115], v[170:173], v[178:181], 0
	v_mfma_f32_16x16x32_bf16 v[100:103], v[162:165], v[196:199], 0
	v_mfma_f32_16x16x32_bf16 v[96:99], v[170:173], v[196:199], 0
	v_mfma_f32_16x16x32_bf16 v[84:87], v[162:165], v[204:207], 0
	v_mfma_f32_16x16x32_bf16 v[80:83], v[170:173], v[204:207], 0
	v_mfma_f32_16x16x32_bf16 v[68:71], v[162:165], v[212:215], 0
	v_mfma_f32_16x16x32_bf16 v[64:67], v[170:173], v[212:215], 0
	v_mfma_f32_16x16x32_bf16 v[116:119], v[166:169], v[192:195], v[116:119]
	v_mfma_f32_16x16x32_bf16 v[112:115], v[174:177], v[192:195], v[112:115]
	v_mfma_f32_16x16x32_bf16 v[100:103], v[166:169], v[200:203], v[100:103]
	v_mfma_f32_16x16x32_bf16 v[96:99], v[174:177], v[200:203], v[96:99]
	v_mfma_f32_16x16x32_bf16 v[84:87], v[166:169], v[208:211], v[84:87]
	v_mfma_f32_16x16x32_bf16 v[80:83], v[174:177], v[208:211], v[80:83]
	v_mfma_f32_16x16x32_bf16 v[68:71], v[166:169], v[216:219], v[68:71]
	v_mfma_f32_16x16x32_bf16 v[64:67], v[174:177], v[216:219], v[64:67]
	s_barrier
	s_setprio 0
	s_add_i32 s57, s51, s35
	v_lshl_add_u64 v[182:183], s[38:39], 0, v[148:149]
	s_mov_b32 m0, s57
	ds_read_b128 v[178:181], v188 offset:16384
	ds_read_b128 v[192:195], v188 offset:17408
	ds_read_b128 v[196:199], v188 offset:18432
	ds_read_b128 v[200:203], v188 offset:19456
	ds_read_b128 v[204:207], v188 offset:20480
	ds_read_b128 v[208:211], v188 offset:21504
	ds_read_b128 v[212:215], v188 offset:22528
	ds_read_b128 v[216:219], v188 offset:23552
	global_load_lds_dwordx4 v[182:183], off
	s_add_i32 m0, s57, 0x2000
	s_add_u32 s58, s38, 0x80000
	v_lshl_add_u64 v[220:221], s[38:39], 0, v[144:145]
	s_addc_u32 s59, s39, 0
	s_add_i32 s57, s52, s35
	global_load_lds_dwordx4 v[220:221], off
	v_lshl_add_u64 v[222:223], s[58:59], 0, v[148:149]
	s_mov_b32 m0, s57
	v_lshl_add_u64 v[224:225], s[40:41], 0, v[146:147]
	global_load_lds_dwordx4 v[222:223], off
	s_add_i32 m0, s57, 0x2000
	v_lshl_add_u64 v[222:223], s[58:59], 0, v[144:145]
	global_load_lds_dwordx4 v[222:223], off
	s_mov_b32 m0, s42
	v_lshl_add_u64 v[222:223], s[40:41], 0, v[150:151]
	global_load_lds_dwordx4 v[222:223], off
	s_mov_b32 m0, s43
	s_nop 0
	global_load_lds_dwordx4 v[224:225], off
	s_waitcnt vmcnt(8) lgkmcnt(0)
	s_setprio 1
	s_barrier
	v_mfma_f32_16x16x32_bf16 v[60:63], v[128:131], v[178:181], 0
	v_mfma_f32_16x16x32_bf16 v[56:59], v[136:139], v[178:181], 0
	v_mfma_f32_16x16x32_bf16 v[44:47], v[128:131], v[196:199], 0
	v_mfma_f32_16x16x32_bf16 v[40:43], v[136:139], v[196:199], 0
	v_mfma_f32_16x16x32_bf16 v[28:31], v[128:131], v[204:207], 0
	v_mfma_f32_16x16x32_bf16 v[24:27], v[136:139], v[204:207], 0
	v_mfma_f32_16x16x32_bf16 v[12:15], v[128:131], v[212:215], 0
	v_mfma_f32_16x16x32_bf16 v[8:11], v[136:139], v[212:215], 0
	v_mfma_f32_16x16x32_bf16 v[60:63], v[132:135], v[192:195], v[60:63]
	v_mfma_f32_16x16x32_bf16 v[56:59], v[140:143], v[192:195], v[56:59]
	v_mfma_f32_16x16x32_bf16 v[44:47], v[132:135], v[200:203], v[44:47]
	v_mfma_f32_16x16x32_bf16 v[40:43], v[140:143], v[200:203], v[40:43]
	v_mfma_f32_16x16x32_bf16 v[28:31], v[132:135], v[208:211], v[28:31]
	v_mfma_f32_16x16x32_bf16 v[24:27], v[140:143], v[208:211], v[24:27]
	v_mfma_f32_16x16x32_bf16 v[12:15], v[132:135], v[216:219], v[12:15]
	v_mfma_f32_16x16x32_bf16 v[8:11], v[140:143], v[216:219], v[8:11]
	s_setprio 0
	s_setprio 1
	v_mfma_f32_16x16x32_bf16 v[52:55], v[162:165], v[178:181], 0
	v_mfma_f32_16x16x32_bf16 v[48:51], v[170:173], v[178:181], 0
	v_mfma_f32_16x16x32_bf16 v[36:39], v[162:165], v[196:199], 0
	v_mfma_f32_16x16x32_bf16 v[32:35], v[170:173], v[196:199], 0
	v_mfma_f32_16x16x32_bf16 v[20:23], v[162:165], v[204:207], 0
	v_mfma_f32_16x16x32_bf16 v[16:19], v[170:173], v[204:207], 0
	v_mfma_f32_16x16x32_bf16 v[4:7], v[162:165], v[212:215], 0
	v_mfma_f32_16x16x32_bf16 v[0:3], v[170:173], v[212:215], 0
	v_mfma_f32_16x16x32_bf16 v[52:55], v[166:169], v[192:195], v[52:55]
	v_mfma_f32_16x16x32_bf16 v[48:51], v[174:177], v[192:195], v[48:51]
	v_mfma_f32_16x16x32_bf16 v[36:39], v[166:169], v[200:203], v[36:39]
	v_mfma_f32_16x16x32_bf16 v[32:35], v[174:177], v[200:203], v[32:35]
	v_mfma_f32_16x16x32_bf16 v[20:23], v[166:169], v[208:211], v[20:23]
	v_mfma_f32_16x16x32_bf16 v[16:19], v[174:177], v[208:211], v[16:19]
	v_mfma_f32_16x16x32_bf16 v[4:7], v[166:169], v[216:219], v[4:7]
	v_mfma_f32_16x16x32_bf16 v[0:3], v[174:177], v[216:219], v[0:3]
	s_barrier
	s_setprio 0
	s_branch .Lpeel_mid_p4
	s_nop 0
	s_nop 0
	s_nop 0
	s_nop 0
	s_nop 0
	s_nop 0
	s_nop 0
	s_nop 0
.LBB0_672:
	ds_read_b128 v[128:131], v185
	ds_read_b128 v[132:135], v185 offset:1024
	ds_read_b128 v[136:139], v185 offset:2048
	ds_read_b128 v[140:143], v185 offset:3072
	ds_read_b128 v[162:165], v186
	ds_read_b128 v[166:169], v186 offset:1024
	ds_read_b128 v[170:173], v186 offset:2048
	ds_read_b128 v[174:177], v186 offset:3072
	s_add_u32 s38, s6, 0xfff80080
	s_addc_u32 s39, s7, -1
	s_cmp_eq_u32 s56, 28
	s_cselect_b32 s41, s27, s39
	s_cselect_b32 s40, s26, s38
	s_cselect_b32 s39, s23, s25
	s_cselect_b32 s38, s22, s5
	v_lshl_add_u64 v[182:183], s[6:7], 0, v[158:159]
	s_add_i32 m0, s42, 0xc000
	ds_read_b128 v[178:181], v188
	ds_read_b128 v[192:195], v188 offset:1024
	ds_read_b128 v[196:199], v188 offset:2048
	ds_read_b128 v[200:203], v188 offset:3072
	ds_read_b128 v[204:207], v188 offset:4096
	ds_read_b128 v[208:211], v188 offset:5120
	ds_read_b128 v[212:215], v188 offset:6144
	ds_read_b128 v[216:219], v188 offset:7168
	global_load_lds_dwordx4 v[182:183], off
	v_lshl_add_u64 v[182:183], s[6:7], 0, v[160:161]
	s_add_i32 m0, s42, 0xe000
	s_nop 0
	global_load_lds_dwordx4 v[182:183], off
	s_waitcnt vmcnt(8) lgkmcnt(0)
	s_setprio 1
	s_barrier
	v_mfma_f32_16x16x32_bf16 v[124:127], v[128:131], v[178:181], v[124:127]
	v_mfma_f32_16x16x32_bf16 v[120:123], v[136:139], v[178:181], v[120:123]
	v_mfma_f32_16x16x32_bf16 v[108:111], v[128:131], v[196:199], v[108:111]
	v_mfma_f32_16x16x32_bf16 v[104:107], v[136:139], v[196:199], v[104:107]
	v_mfma_f32_16x16x32_bf16 v[92:95], v[128:131], v[204:207], v[92:95]
	v_mfma_f32_16x16x32_bf16 v[88:91], v[136:139], v[204:207], v[88:91]
	v_mfma_f32_16x16x32_bf16 v[76:79], v[128:131], v[212:215], v[76:79]
	v_mfma_f32_16x16x32_bf16 v[72:75], v[136:139], v[212:215], v[72:75]
	v_mfma_f32_16x16x32_bf16 v[124:127], v[132:135], v[192:195], v[124:127]
	v_mfma_f32_16x16x32_bf16 v[120:123], v[140:143], v[192:195], v[120:123]
	v_mfma_f32_16x16x32_bf16 v[108:111], v[132:135], v[200:203], v[108:111]
	v_mfma_f32_16x16x32_bf16 v[104:107], v[140:143], v[200:203], v[104:107]
	v_mfma_f32_16x16x32_bf16 v[92:95], v[132:135], v[208:211], v[92:95]
	v_mfma_f32_16x16x32_bf16 v[88:91], v[140:143], v[208:211], v[88:91]
	v_mfma_f32_16x16x32_bf16 v[76:79], v[132:135], v[216:219], v[76:79]
	v_mfma_f32_16x16x32_bf16 v[72:75], v[140:143], v[216:219], v[72:75]
	s_setprio 0
	s_setprio 1
	v_mfma_f32_16x16x32_bf16 v[116:119], v[162:165], v[178:181], v[116:119]
	v_mfma_f32_16x16x32_bf16 v[112:115], v[170:173], v[178:181], v[112:115]
	v_mfma_f32_16x16x32_bf16 v[100:103], v[162:165], v[196:199], v[100:103]
	v_mfma_f32_16x16x32_bf16 v[96:99], v[170:173], v[196:199], v[96:99]
	v_mfma_f32_16x16x32_bf16 v[84:87], v[162:165], v[204:207], v[84:87]
	v_mfma_f32_16x16x32_bf16 v[80:83], v[170:173], v[204:207], v[80:83]
	v_mfma_f32_16x16x32_bf16 v[68:71], v[162:165], v[212:215], v[68:71]
	v_mfma_f32_16x16x32_bf16 v[64:67], v[170:173], v[212:215], v[64:67]
	v_mfma_f32_16x16x32_bf16 v[116:119], v[166:169], v[192:195], v[116:119]
	v_mfma_f32_16x16x32_bf16 v[112:115], v[174:177], v[192:195], v[112:115]
	v_mfma_f32_16x16x32_bf16 v[100:103], v[166:169], v[200:203], v[100:103]
	v_mfma_f32_16x16x32_bf16 v[96:99], v[174:177], v[200:203], v[96:99]
	v_mfma_f32_16x16x32_bf16 v[84:87], v[166:169], v[208:211], v[84:87]
	v_mfma_f32_16x16x32_bf16 v[80:83], v[174:177], v[208:211], v[80:83]
	v_mfma_f32_16x16x32_bf16 v[68:71], v[166:169], v[216:219], v[68:71]
	v_mfma_f32_16x16x32_bf16 v[64:67], v[174:177], v[216:219], v[64:67]
	s_barrier
	s_setprio 0
	s_add_i32 s57, s51, s35
	v_lshl_add_u64 v[182:183], s[38:39], 0, v[148:149]
	s_mov_b32 m0, s57
	ds_read_b128 v[178:181], v188 offset:16384
	ds_read_b128 v[192:195], v188 offset:17408
	ds_read_b128 v[196:199], v188 offset:18432
	ds_read_b128 v[200:203], v188 offset:19456
	ds_read_b128 v[204:207], v188 offset:20480
	ds_read_b128 v[208:211], v188 offset:21504
	ds_read_b128 v[212:215], v188 offset:22528
	ds_read_b128 v[216:219], v188 offset:23552
	global_load_lds_dwordx4 v[182:183], off
	s_add_i32 m0, s57, 0x2000
	s_add_u32 s58, s38, 0x80000
	v_lshl_add_u64 v[220:221], s[38:39], 0, v[144:145]
	s_addc_u32 s59, s39, 0
	s_add_i32 s57, s52, s35
	global_load_lds_dwordx4 v[220:221], off
	v_lshl_add_u64 v[222:223], s[58:59], 0, v[148:149]
	s_mov_b32 m0, s57
	v_lshl_add_u64 v[224:225], s[40:41], 0, v[146:147]
	global_load_lds_dwordx4 v[222:223], off
	s_add_i32 m0, s57, 0x2000
	v_lshl_add_u64 v[222:223], s[58:59], 0, v[144:145]
	global_load_lds_dwordx4 v[222:223], off
	s_mov_b32 m0, s42
	v_lshl_add_u64 v[222:223], s[40:41], 0, v[150:151]
	global_load_lds_dwordx4 v[222:223], off
	s_mov_b32 m0, s43
	s_nop 0
	global_load_lds_dwordx4 v[224:225], off
	s_waitcnt vmcnt(8) lgkmcnt(0)
	s_setprio 1
	s_barrier
	v_mfma_f32_16x16x32_bf16 v[60:63], v[128:131], v[178:181], v[60:63]
	v_mfma_f32_16x16x32_bf16 v[56:59], v[136:139], v[178:181], v[56:59]
	v_mfma_f32_16x16x32_bf16 v[44:47], v[128:131], v[196:199], v[44:47]
	v_mfma_f32_16x16x32_bf16 v[40:43], v[136:139], v[196:199], v[40:43]
	v_mfma_f32_16x16x32_bf16 v[28:31], v[128:131], v[204:207], v[28:31]
	v_mfma_f32_16x16x32_bf16 v[24:27], v[136:139], v[204:207], v[24:27]
	v_mfma_f32_16x16x32_bf16 v[12:15], v[128:131], v[212:215], v[12:15]
	v_mfma_f32_16x16x32_bf16 v[8:11], v[136:139], v[212:215], v[8:11]
	v_mfma_f32_16x16x32_bf16 v[60:63], v[132:135], v[192:195], v[60:63]
	v_mfma_f32_16x16x32_bf16 v[56:59], v[140:143], v[192:195], v[56:59]
	v_mfma_f32_16x16x32_bf16 v[44:47], v[132:135], v[200:203], v[44:47]
	v_mfma_f32_16x16x32_bf16 v[40:43], v[140:143], v[200:203], v[40:43]
	v_mfma_f32_16x16x32_bf16 v[28:31], v[132:135], v[208:211], v[28:31]
	v_mfma_f32_16x16x32_bf16 v[24:27], v[140:143], v[208:211], v[24:27]
	v_mfma_f32_16x16x32_bf16 v[12:15], v[132:135], v[216:219], v[12:15]
	v_mfma_f32_16x16x32_bf16 v[8:11], v[140:143], v[216:219], v[8:11]
	s_setprio 0
	s_setprio 1
	v_mfma_f32_16x16x32_bf16 v[52:55], v[162:165], v[178:181], v[52:55]
	v_mfma_f32_16x16x32_bf16 v[48:51], v[170:173], v[178:181], v[48:51]
	v_mfma_f32_16x16x32_bf16 v[36:39], v[162:165], v[196:199], v[36:39]
	v_mfma_f32_16x16x32_bf16 v[32:35], v[170:173], v[196:199], v[32:35]
	v_mfma_f32_16x16x32_bf16 v[20:23], v[162:165], v[204:207], v[20:23]
	v_mfma_f32_16x16x32_bf16 v[16:19], v[170:173], v[204:207], v[16:19]
	v_mfma_f32_16x16x32_bf16 v[4:7], v[162:165], v[212:215], v[4:7]
	v_mfma_f32_16x16x32_bf16 v[0:3], v[170:173], v[212:215], v[0:3]
	v_mfma_f32_16x16x32_bf16 v[52:55], v[166:169], v[192:195], v[52:55]
	v_mfma_f32_16x16x32_bf16 v[48:51], v[174:177], v[192:195], v[48:51]
	v_mfma_f32_16x16x32_bf16 v[36:39], v[166:169], v[200:203], v[36:39]
	v_mfma_f32_16x16x32_bf16 v[32:35], v[174:177], v[200:203], v[32:35]
	v_mfma_f32_16x16x32_bf16 v[20:23], v[166:169], v[208:211], v[20:23]
	v_mfma_f32_16x16x32_bf16 v[16:19], v[174:177], v[208:211], v[16:19]
	v_mfma_f32_16x16x32_bf16 v[4:7], v[166:169], v[216:219], v[4:7]
	v_mfma_f32_16x16x32_bf16 v[0:3], v[174:177], v[216:219], v[0:3]
	s_barrier
	s_setprio 0
.Lpeel_mid_p4:
	s_add_i32 s57, 0, 0x18000
	s_add_i32 s58, 0, 0x1c000
	v_add_u32_e32 v140, s57, v184
	v_add_u32_e32 v174, s58, v184
	ds_read_b128 v[128:131], v140
	ds_read_b128 v[132:135], v140 offset:1024
	ds_read_b128 v[136:139], v140 offset:2048
	ds_read_b128 v[140:143], v140 offset:3072
	ds_read_b128 v[162:165], v174
	ds_read_b128 v[166:169], v174 offset:1024
	ds_read_b128 v[170:173], v174 offset:2048
	ds_read_b128 v[174:177], v174 offset:3072
	s_add_u32 s40, s40, 0x80000
	s_addc_u32 s41, s41, 0
	s_mov_b32 m0, s44
	v_lshl_add_u64 v[226:227], s[40:41], 0, v[150:151]
	ds_read_b128 v[178:181], v188 offset:32768
	ds_read_b128 v[192:195], v188 offset:33792
	ds_read_b128 v[196:199], v188 offset:34816
	ds_read_b128 v[200:203], v188 offset:35840
	ds_read_b128 v[204:207], v188 offset:36864
	ds_read_b128 v[208:211], v188 offset:37888
	ds_read_b128 v[212:215], v188 offset:38912
	ds_read_b128 v[216:219], v188 offset:39936
	global_load_lds_dwordx4 v[226:227], off
	v_lshl_add_u64 v[226:227], s[40:41], 0, v[146:147]
	s_mov_b32 m0, s45
	s_nop 0
	global_load_lds_dwordx4 v[226:227], off
	s_waitcnt vmcnt(8) lgkmcnt(0)
	s_setprio 1
	s_barrier
	v_mfma_f32_16x16x32_bf16 v[124:127], v[128:131], v[178:181], v[124:127]
	v_mfma_f32_16x16x32_bf16 v[120:123], v[136:139], v[178:181], v[120:123]
	v_mfma_f32_16x16x32_bf16 v[108:111], v[128:131], v[196:199], v[108:111]
	v_mfma_f32_16x16x32_bf16 v[104:107], v[136:139], v[196:199], v[104:107]
	v_mfma_f32_16x16x32_bf16 v[92:95], v[128:131], v[204:207], v[92:95]
	v_mfma_f32_16x16x32_bf16 v[88:91], v[136:139], v[204:207], v[88:91]
	v_mfma_f32_16x16x32_bf16 v[76:79], v[128:131], v[212:215], v[76:79]
	v_mfma_f32_16x16x32_bf16 v[72:75], v[136:139], v[212:215], v[72:75]
	v_mfma_f32_16x16x32_bf16 v[124:127], v[132:135], v[192:195], v[124:127]
	v_mfma_f32_16x16x32_bf16 v[120:123], v[140:143], v[192:195], v[120:123]
	v_mfma_f32_16x16x32_bf16 v[108:111], v[132:135], v[200:203], v[108:111]
	v_mfma_f32_16x16x32_bf16 v[104:107], v[140:143], v[200:203], v[104:107]
	v_mfma_f32_16x16x32_bf16 v[92:95], v[132:135], v[208:211], v[92:95]
	v_mfma_f32_16x16x32_bf16 v[88:91], v[140:143], v[208:211], v[88:91]
	v_mfma_f32_16x16x32_bf16 v[76:79], v[132:135], v[216:219], v[76:79]
	v_mfma_f32_16x16x32_bf16 v[72:75], v[140:143], v[216:219], v[72:75]
	s_setprio 0
	s_setprio 1
	v_mfma_f32_16x16x32_bf16 v[116:119], v[162:165], v[178:181], v[116:119]
	v_mfma_f32_16x16x32_bf16 v[112:115], v[170:173], v[178:181], v[112:115]
	v_mfma_f32_16x16x32_bf16 v[100:103], v[162:165], v[196:199], v[100:103]
	v_mfma_f32_16x16x32_bf16 v[96:99], v[170:173], v[196:199], v[96:99]
	v_mfma_f32_16x16x32_bf16 v[84:87], v[162:165], v[204:207], v[84:87]
	v_mfma_f32_16x16x32_bf16 v[80:83], v[170:173], v[204:207], v[80:83]
	v_mfma_f32_16x16x32_bf16 v[68:71], v[162:165], v[212:215], v[68:71]
	v_mfma_f32_16x16x32_bf16 v[64:67], v[170:173], v[212:215], v[64:67]
	v_mfma_f32_16x16x32_bf16 v[116:119], v[166:169], v[192:195], v[116:119]
	v_mfma_f32_16x16x32_bf16 v[112:115], v[174:177], v[192:195], v[112:115]
	v_mfma_f32_16x16x32_bf16 v[100:103], v[166:169], v[200:203], v[100:103]
	v_mfma_f32_16x16x32_bf16 v[96:99], v[174:177], v[200:203], v[96:99]
	v_mfma_f32_16x16x32_bf16 v[84:87], v[166:169], v[208:211], v[84:87]
	v_mfma_f32_16x16x32_bf16 v[80:83], v[174:177], v[208:211], v[80:83]
	v_mfma_f32_16x16x32_bf16 v[68:71], v[166:169], v[216:219], v[68:71]
	v_mfma_f32_16x16x32_bf16 v[64:67], v[174:177], v[216:219], v[64:67]
	s_barrier
	s_setprio 0
	s_add_i32 s40, s57, s35
	v_lshl_add_u64 v[182:183], v[182:183], 0, s[14:15]
	s_mov_b32 m0, s40
	ds_read_b128 v[178:181], v188 offset:49152
	ds_read_b128 v[192:195], v188 offset:50176
	ds_read_b128 v[196:199], v188 offset:51200
	ds_read_b128 v[200:203], v188 offset:52224
	ds_read_b128 v[204:207], v188 offset:53248
	ds_read_b128 v[208:211], v188 offset:54272
	ds_read_b128 v[212:215], v188 offset:55296
	ds_read_b128 v[216:219], v188 offset:56320
	global_load_lds_dwordx4 v[182:183], off
	s_add_i32 m0, s40, 0x2000
	s_add_u32 s38, s38, 0x80080
	v_lshl_add_u64 v[182:183], v[220:221], 0, s[14:15]
	s_addc_u32 s39, s39, 0
	s_add_i32 s40, s58, s35
	global_load_lds_dwordx4 v[182:183], off
	s_mov_b32 m0, s40
	v_lshl_add_u64 v[182:183], s[38:39], 0, v[148:149]
	global_load_lds_dwordx4 v[182:183], off
	s_add_i32 m0, s40, 0x2000
	v_lshl_add_u64 v[182:183], s[38:39], 0, v[144:145]
	global_load_lds_dwordx4 v[182:183], off
	s_mov_b32 m0, s49
	v_lshl_add_u64 v[182:183], v[222:223], 0, s[14:15]
	global_load_lds_dwordx4 v[182:183], off
	s_mov_b32 m0, s50
	v_lshl_add_u64 v[182:183], v[224:225], 0, s[14:15]
	global_load_lds_dwordx4 v[182:183], off
	s_waitcnt vmcnt(8) lgkmcnt(0)
	s_setprio 1
	s_barrier
	v_mfma_f32_16x16x32_bf16 v[60:63], v[128:131], v[178:181], v[60:63]
	v_mfma_f32_16x16x32_bf16 v[56:59], v[136:139], v[178:181], v[56:59]
	v_mfma_f32_16x16x32_bf16 v[44:47], v[128:131], v[196:199], v[44:47]
	v_mfma_f32_16x16x32_bf16 v[40:43], v[136:139], v[196:199], v[40:43]
	v_mfma_f32_16x16x32_bf16 v[28:31], v[128:131], v[204:207], v[28:31]
	v_mfma_f32_16x16x32_bf16 v[24:27], v[136:139], v[204:207], v[24:27]
	v_mfma_f32_16x16x32_bf16 v[12:15], v[128:131], v[212:215], v[12:15]
	v_mfma_f32_16x16x32_bf16 v[8:11], v[136:139], v[212:215], v[8:11]
	v_mfma_f32_16x16x32_bf16 v[60:63], v[132:135], v[192:195], v[60:63]
	v_mfma_f32_16x16x32_bf16 v[56:59], v[140:143], v[192:195], v[56:59]
	v_mfma_f32_16x16x32_bf16 v[44:47], v[132:135], v[200:203], v[44:47]
	v_mfma_f32_16x16x32_bf16 v[40:43], v[140:143], v[200:203], v[40:43]
	v_mfma_f32_16x16x32_bf16 v[28:31], v[132:135], v[208:211], v[28:31]
	v_mfma_f32_16x16x32_bf16 v[24:27], v[140:143], v[208:211], v[24:27]
	v_mfma_f32_16x16x32_bf16 v[12:15], v[132:135], v[216:219], v[12:15]
	v_mfma_f32_16x16x32_bf16 v[8:11], v[140:143], v[216:219], v[8:11]
	s_setprio 0
	s_setprio 1
	v_mfma_f32_16x16x32_bf16 v[52:55], v[162:165], v[178:181], v[52:55]
	v_mfma_f32_16x16x32_bf16 v[48:51], v[170:173], v[178:181], v[48:51]
	v_mfma_f32_16x16x32_bf16 v[36:39], v[162:165], v[196:199], v[36:39]
	v_mfma_f32_16x16x32_bf16 v[32:35], v[170:173], v[196:199], v[32:35]
	s_add_i32 s56, s56, 2
	v_mfma_f32_16x16x32_bf16 v[20:23], v[162:165], v[204:207], v[20:23]
	s_add_u32 s6, s6, 0x100
	v_mfma_f32_16x16x32_bf16 v[16:19], v[170:173], v[204:207], v[16:19]
	s_addc_u32 s7, s7, 0
	v_mfma_f32_16x16x32_bf16 v[4:7], v[162:165], v[212:215], v[4:7]
	s_add_u32 s5, s5, 0x100
	v_mfma_f32_16x16x32_bf16 v[0:3], v[170:173], v[212:215], v[0:3]
	s_addc_u32 s25, s25, 0
	v_mfma_f32_16x16x32_bf16 v[52:55], v[166:169], v[192:195], v[52:55]
	s_cmp_gt_u32 s56, 29
	v_mfma_f32_16x16x32_bf16 v[48:51], v[174:177], v[192:195], v[48:51]
	v_mfma_f32_16x16x32_bf16 v[36:39], v[166:169], v[200:203], v[36:39]
	v_mfma_f32_16x16x32_bf16 v[32:35], v[174:177], v[200:203], v[32:35]
	v_mfma_f32_16x16x32_bf16 v[20:23], v[166:169], v[208:211], v[20:23]
	v_mfma_f32_16x16x32_bf16 v[16:19], v[174:177], v[208:211], v[16:19]
	v_mfma_f32_16x16x32_bf16 v[4:7], v[166:169], v[216:219], v[4:7]
	v_mfma_f32_16x16x32_bf16 v[0:3], v[174:177], v[216:219], v[0:3]
	s_barrier
	s_setprio 0
	s_cbranch_scc0 .LBB0_672
	s_and_b64 vcc, exec, s[18:19]
	s_cbranch_vccz .LBB0_675
	s_barrier
